# speedup vs baseline: 1.0051x; 1.0048x over previous
; #define PG8_STAGE(bufoff, gbase, voff) do { _Pragma("unroll") for (int _i = 0; _i < 2; ++_i) \
;         __builtin_amdgcn_global_load_lds((const unsigned*)((const char*)(gbase) + (voff)[_i]), (PG8_LAS unsigned*)(lds + (bufoff) + ldsw + _i * 8192), 16, 0, 0); } while (0)
; #define PG8_LDA(dst, b, h) do { _Pragma("unroll") for (int m = 0; m < 4; ++m) _Pragma("unroll") for (int k = 0; k < 2; ++k) dst[m][k] = *(const PG8_LAS bf16x8*)(lds + PG8_SA(b, h) + aoff + m * 2048 + k * 1024); } while (0)
; #define PG8_LDB(dst, b, h) do { _Pragma("unroll") for (int n = 0; n < 2; ++n) _Pragma("unroll") for (int k = 0; k < 2; ++k) dst[n][k] = *(const PG8_LAS bf16x8*)(lds + PG8_SB(b, h) + boff + n * 2048 + k * 1024); } while (0)
; #define PG8_WAIT_V(n) asm volatile("s_waitcnt vmcnt(" #n ")" ::: "memory")
; #define PG8_WAIT_L(n) asm volatile("s_waitcnt lgkmcnt(" #n ")" ::: "memory")
; #define PG8_BAR __builtin_amdgcn_s_barrier()
; template <class Epi, class Sched, bool ALIGN_EPI = false, bool SP2 = false>
; __device__ __forceinline__ void gemm_phase(PG8_LAS unsigned char* lds, const Gemm g, const Sched& S, const Epi& E) {
;     ...
;         const bool has_next = S.next(ui + 1, nxt);
;         const char* nA = has_next ? (const char*)g.A + (size_t)nxt.pm * tstep + (size_t)nxt.kh * K * 2 : cA; const char* nB = has_next ? (const char*)g.Bt + (size_t)nxt.pn * tstep + (size_t)nxt.kh * K * 2 : cB;
;         for (int t = 0; t < nt; t += 2) {
;             const bool last = (t == nt - 2);
;             const char* a1 = cA + (size_t)(t + 1) * kstep;
;             const char* a2 = last ? nA : cA + (size_t)(t + 2) * kstep; const char* b2 = last ? nB : cB + (size_t)(t + 2) * kstep;
;             const char* a3 = a2 + kstep; const char* b3 = b2 + kstep;
;             if (last && has_next) S.a_ready(nxt);
;             if constexpr (SP2) {
;             PG8_LDB(B0, 0, 0); PG8_LDB(B1, 0, 1); PG8_SCHED; PG8_LDA(At, 0, 0); PG8_STAGE(PG8_SA(1, 1), a1 + hstep, voffA);
;             PG8_WAIT_V(8); PG8_WAIT_L(0); PG8_BAR; PG8_MMA(0, 0, At, B0); PG8_MMA(0, 1, At, B1); PG8_BAR; PG8_SCHED;
;     ...
;         if (!partial)
; #pragma unroll
;         for (int a = 0; a < 2; ++a)
; #pragma unroll
;             for (int b = 0; b < 2; ++b)
; #pragma unroll
;                 for (int m = 0; m < 4; ++m)
; #pragma unroll
;                     for (int n = 0; n < 2; ++n) acc[a][b][m][n] = (f32x4){0.f, 0.f, 0.f, 0.f};
.LBB0_966:
	s_ashr_i32 s25, s24, 31
	s_lshl_b64 s[10:11], s[24:25], 19
	s_add_u32 s23, s78, s10
	s_addc_u32 s25, s79, s11
	s_and_b64 s[10:11], s[4:5], exec
	s_cselect_b32 s27, s25, s7
	s_cselect_b32 s26, s23, s6
	s_ashr_i32 s23, s22, 31
	s_lshl_b64 s[10:11], s[22:23], 19
	s_add_u32 s23, s30, s10
	s_addc_u32 s25, s31, s11
	s_and_b64 s[10:11], s[4:5], exec
	s_cselect_b32 s29, s25, s9
	s_cselect_b32 s28, s23, s8
	s_add_u32 s6, s6, 0x40080
	s_addc_u32 s7, s7, 0
	s_add_u32 s23, s8, 0x100
	v_mov_b32_e32 v0, 0
	s_addc_u32 s25, s9, 0
	s_mov_b32 s57, -2
	v_mov_b32_e32 v1, v0
	v_mov_b32_e32 v2, v0
	v_mov_b32_e32 v3, v0
	v_mov_b32_e32 v4, v0
	v_mov_b32_e32 v5, v0
	v_mov_b32_e32 v6, v0
	v_mov_b32_e32 v7, v0
	v_mov_b32_e32 v16, v0
	v_mov_b32_e32 v17, v0
	v_mov_b32_e32 v18, v0
	v_mov_b32_e32 v19, v0
	v_mov_b32_e32 v20, v0
	v_mov_b32_e32 v21, v0
	v_mov_b32_e32 v22, v0
	v_mov_b32_e32 v23, v0
	v_mov_b32_e32 v32, v0
	v_mov_b32_e32 v33, v0
	v_mov_b32_e32 v34, v0
	v_mov_b32_e32 v35, v0
	v_mov_b32_e32 v36, v0
	v_mov_b32_e32 v37, v0
	v_mov_b32_e32 v38, v0
	v_mov_b32_e32 v39, v0
	v_mov_b32_e32 v48, v0
	v_mov_b32_e32 v49, v0
	v_mov_b32_e32 v50, v0
	v_mov_b32_e32 v51, v0
	v_mov_b32_e32 v52, v0
	v_mov_b32_e32 v53, v0
	v_mov_b32_e32 v54, v0
	v_mov_b32_e32 v55, v0
	v_mov_b32_e32 v8, v0
	v_mov_b32_e32 v9, v0
	v_mov_b32_e32 v10, v0
	v_mov_b32_e32 v11, v0
	v_mov_b32_e32 v12, v0
	v_mov_b32_e32 v13, v0
	v_mov_b32_e32 v14, v0
	v_mov_b32_e32 v15, v0
	v_mov_b32_e32 v24, v0
	v_mov_b32_e32 v25, v0
	v_mov_b32_e32 v26, v0
	v_mov_b32_e32 v27, v0
	v_mov_b32_e32 v28, v0
	v_mov_b32_e32 v29, v0
	v_mov_b32_e32 v30, v0
	v_mov_b32_e32 v31, v0
	v_mov_b32_e32 v40, v0
	v_mov_b32_e32 v41, v0
	v_mov_b32_e32 v42, v0
	v_mov_b32_e32 v43, v0
	v_mov_b32_e32 v44, v0
	v_mov_b32_e32 v45, v0
	v_mov_b32_e32 v46, v0
	v_mov_b32_e32 v47, v0
	v_mov_b32_e32 v56, v0
	v_mov_b32_e32 v57, v0
	v_mov_b32_e32 v58, v0
	v_mov_b32_e32 v59, v0
	v_mov_b32_e32 v60, v0
	v_mov_b32_e32 v61, v0
	v_mov_b32_e32 v62, v0
	v_mov_b32_e32 v63, v0
	v_mov_b32_e32 v64, v0
	v_mov_b32_e32 v65, v0
	v_mov_b32_e32 v66, v0
	v_mov_b32_e32 v67, v0
	v_mov_b32_e32 v68, v0
	v_mov_b32_e32 v69, v0
	v_mov_b32_e32 v70, v0
	v_mov_b32_e32 v71, v0
	v_mov_b32_e32 v80, v0
	v_mov_b32_e32 v81, v0
	v_mov_b32_e32 v82, v0
	v_mov_b32_e32 v83, v0
	v_mov_b32_e32 v84, v0
	v_mov_b32_e32 v85, v0
	v_mov_b32_e32 v86, v0
	v_mov_b32_e32 v87, v0
	v_mov_b32_e32 v96, v0
	v_mov_b32_e32 v97, v0
	v_mov_b32_e32 v98, v0
	v_mov_b32_e32 v99, v0
	v_mov_b32_e32 v100, v0
	v_mov_b32_e32 v101, v0
	v_mov_b32_e32 v102, v0
	v_mov_b32_e32 v103, v0
	v_mov_b32_e32 v112, v0
	v_mov_b32_e32 v113, v0
	v_mov_b32_e32 v114, v0
	v_mov_b32_e32 v115, v0
	v_mov_b32_e32 v116, v0
	v_mov_b32_e32 v117, v0
	v_mov_b32_e32 v118, v0
	v_mov_b32_e32 v119, v0
	v_mov_b32_e32 v72, v0
	v_mov_b32_e32 v73, v0
	v_mov_b32_e32 v74, v0
	v_mov_b32_e32 v75, v0
	v_mov_b32_e32 v76, v0
	v_mov_b32_e32 v77, v0
	v_mov_b32_e32 v78, v0
	v_mov_b32_e32 v79, v0
	v_mov_b32_e32 v88, v0
	v_mov_b32_e32 v89, v0
	v_mov_b32_e32 v90, v0
	v_mov_b32_e32 v91, v0
	v_mov_b32_e32 v92, v0
	v_mov_b32_e32 v93, v0
	v_mov_b32_e32 v94, v0
	v_mov_b32_e32 v95, v0
	v_mov_b32_e32 v104, v0
	v_mov_b32_e32 v105, v0
	v_mov_b32_e32 v106, v0
	v_mov_b32_e32 v107, v0
	v_mov_b32_e32 v108, v0
	v_mov_b32_e32 v109, v0
	v_mov_b32_e32 v110, v0
	v_mov_b32_e32 v111, v0
	v_mov_b32_e32 v120, v0
	v_mov_b32_e32 v121, v0
	v_mov_b32_e32 v122, v0
	v_mov_b32_e32 v123, v0
	v_mov_b32_e32 v124, v0
	v_mov_b32_e32 v125, v0
	v_mov_b32_e32 v126, v0
	v_mov_b32_e32 v127, v0
	s_cmp_eq_u32 s48, 1
	s_cbranch_scc1 .LBB0_967
.Lg7_peel:
	ds_read_b128 v[144:147], v161
	ds_read_b128 v[172:175], v161 offset:1024
	ds_read_b128 v[176:179], v161 offset:2048
	ds_read_b128 v[196:199], v161 offset:3072
	ds_read_b128 v[200:203], v165
	ds_read_b128 v[204:207], v165 offset:1024
	ds_read_b128 v[208:211], v165 offset:2048
	ds_read_b128 v[212:215], v165 offset:3072
	s_add_u32 s8, s6, 0xfffc0080
	s_addc_u32 s9, s7, -1
	s_cmp_eq_u32 s57, 12
	s_cselect_b32 s11, s27, s9
	s_cselect_b32 s10, s26, s8
	s_cselect_b32 s9, s29, s25
	s_cselect_b32 s8, s28, s23
	v_lshl_add_u64 v[148:149], s[6:7], 0, v[128:129]
	s_add_i32 m0, s36, 0xc000
	ds_read_b128 v[216:219], v169
	ds_read_b128 v[220:223], v169 offset:1024
	ds_read_b128 v[224:227], v169 offset:2048
	ds_read_b128 v[228:231], v169 offset:3072
	ds_read_b128 v[232:235], v169 offset:4096
	ds_read_b128 v[236:239], v169 offset:5120
	ds_read_b128 v[240:243], v169 offset:6144
	ds_read_b128 v[244:247], v169 offset:7168
	global_load_lds_dwordx4 v[148:149], off
	v_lshl_add_u64 v[148:149], s[6:7], 0, v[130:131]
	s_add_i32 m0, s36, 0xe000
	s_nop 0
	global_load_lds_dwordx4 v[148:149], off
	s_waitcnt vmcnt(18)
	s_waitcnt lgkmcnt(0)
	s_barrier
; #define PG8_STAGE(bufoff, gbase, voff) do { _Pragma("unroll") for (int _i = 0; _i < 2; ++_i) \
;         __builtin_amdgcn_global_load_lds((const unsigned*)((const char*)(gbase) + (voff)[_i]), (PG8_LAS unsigned*)(lds + (bufoff) + ldsw + _i * 8192), 16, 0, 0); } while (0)
; #define PG8_LDA(dst, b, h) do { _Pragma("unroll") for (int m = 0; m < 4; ++m) _Pragma("unroll") for (int k = 0; k < 2; ++k) dst[m][k] = *(const PG8_LAS bf16x8*)(lds + PG8_SA(b, h) + aoff + m * 2048 + k * 1024); } while (0)
; #define PG8_MMA(ai, bj, At, Bt) do { __builtin_amdgcn_s_setprio(1); _Pragma("unroll") for (int m = 0; m < 4; ++m) _Pragma("unroll") for (int n = 0; n < 2; ++n) _Pragma("unroll") for (int k = 0; k < 2; ++k) \
;         acc[ai][bj][m][n] = __builtin_amdgcn_mfma_f32_16x16x32_bf16(Bt[n][k], At[m][k], acc[ai][bj][m][n], 0, 0, 0); __builtin_amdgcn_s_setprio(0); } while (0)
; #define PG8_WAIT_V(n) asm volatile("s_waitcnt vmcnt(" #n ")" ::: "memory")
; #define PG8_WAIT_L(n) asm volatile("s_waitcnt lgkmcnt(" #n ")" ::: "memory")
; #define PG8_BAR __builtin_amdgcn_s_barrier()
; #define PG8_SCHED __builtin_amdgcn_sched_barrier(0)
; template <class Epi, class Sched, bool ALIGN_EPI = false, bool SP2 = false>
; __device__ __forceinline__ void gemm_phase(PG8_LAS unsigned char* lds, const Gemm g, const Sched& S, const Epi& E) {
;     ...
;             PG8_WAIT_V(8); PG8_WAIT_L(0); PG8_BAR; PG8_MMA(0, 0, At, B0); PG8_MMA(0, 1, At, B1); PG8_BAR; PG8_SCHED;
;             PG8_LDA(At, 0, 1); PG8_STAGE(PG8_SB(0, 0), b2, voffB); PG8_STAGE(PG8_SB(0, 1), b2 + hstep, voffB); PG8_STAGE(PG8_SA(0, 0), a2, voffA);
;             PG8_WAIT_V(8); PG8_WAIT_L(0); PG8_BAR; PG8_MMA(1, 0, At, B0); PG8_MMA(1, 1, At, B1); PG8_BAR; PG8_SCHED;
	s_setprio 1
	s_waitcnt lgkmcnt(0)
	v_mfma_f32_16x16x32_bf16 v[124:127], v[144:147], v[216:219], v[124:127]
	v_mfma_f32_16x16x32_bf16 v[120:123], v[176:179], v[216:219], v[120:123]
	v_mfma_f32_16x16x32_bf16 v[108:111], v[144:147], v[224:227], v[108:111]
	v_mfma_f32_16x16x32_bf16 v[104:107], v[176:179], v[224:227], v[104:107]
	v_mfma_f32_16x16x32_bf16 v[92:95], v[144:147], v[232:235], v[92:95]
	v_mfma_f32_16x16x32_bf16 v[88:91], v[176:179], v[232:235], v[88:91]
	v_mfma_f32_16x16x32_bf16 v[76:79], v[144:147], v[240:243], v[76:79]
	v_mfma_f32_16x16x32_bf16 v[72:75], v[176:179], v[240:243], v[72:75]
	v_mfma_f32_16x16x32_bf16 v[124:127], v[172:175], v[220:223], v[124:127]
	v_mfma_f32_16x16x32_bf16 v[120:123], v[196:199], v[220:223], v[120:123]
	v_mfma_f32_16x16x32_bf16 v[108:111], v[172:175], v[228:231], v[108:111]
	v_mfma_f32_16x16x32_bf16 v[104:107], v[196:199], v[228:231], v[104:107]
	v_mfma_f32_16x16x32_bf16 v[92:95], v[172:175], v[236:239], v[92:95]
	v_mfma_f32_16x16x32_bf16 v[88:91], v[196:199], v[236:239], v[88:91]
	v_mfma_f32_16x16x32_bf16 v[76:79], v[172:175], v[244:247], v[76:79]
	v_mfma_f32_16x16x32_bf16 v[72:75], v[196:199], v[244:247], v[72:75]
	s_setprio 0
	s_setprio 1
	v_mfma_f32_16x16x32_bf16 v[116:119], v[200:203], v[216:219], v[116:119]
	v_mfma_f32_16x16x32_bf16 v[112:115], v[208:211], v[216:219], v[112:115]
	v_mfma_f32_16x16x32_bf16 v[100:103], v[200:203], v[224:227], v[100:103]
	v_mfma_f32_16x16x32_bf16 v[96:99], v[208:211], v[224:227], v[96:99]
	v_mfma_f32_16x16x32_bf16 v[84:87], v[200:203], v[232:235], v[84:87]
	v_mfma_f32_16x16x32_bf16 v[80:83], v[208:211], v[232:235], v[80:83]
	v_mfma_f32_16x16x32_bf16 v[68:71], v[200:203], v[240:243], v[68:71]
	v_mfma_f32_16x16x32_bf16 v[64:67], v[208:211], v[240:243], v[64:67]
	v_mfma_f32_16x16x32_bf16 v[116:119], v[204:207], v[220:223], v[116:119]
	v_mfma_f32_16x16x32_bf16 v[112:115], v[212:215], v[220:223], v[112:115]
	v_mfma_f32_16x16x32_bf16 v[100:103], v[204:207], v[228:231], v[100:103]
	v_mfma_f32_16x16x32_bf16 v[96:99], v[212:215], v[228:231], v[96:99]
	v_mfma_f32_16x16x32_bf16 v[84:87], v[204:207], v[236:239], v[84:87]
	v_mfma_f32_16x16x32_bf16 v[80:83], v[212:215], v[236:239], v[80:83]
	v_mfma_f32_16x16x32_bf16 v[68:71], v[204:207], v[244:247], v[68:71]
	v_mfma_f32_16x16x32_bf16 v[64:67], v[212:215], v[244:247], v[64:67]
	s_setprio 0
	s_barrier
	s_add_i32 s58, s53, s35
	v_lshl_add_u64 v[148:149], s[8:9], 0, v[138:139]
	s_mov_b32 m0, s58
	ds_read_b128 v[216:219], v169 offset:16384
	ds_read_b128 v[220:223], v169 offset:17408
	ds_read_b128 v[224:227], v169 offset:18432
	ds_read_b128 v[228:231], v169 offset:19456
	ds_read_b128 v[232:235], v169 offset:20480
	ds_read_b128 v[236:239], v169 offset:21504
	ds_read_b128 v[240:243], v169 offset:22528
	ds_read_b128 v[244:247], v169 offset:23552
	global_load_lds_dwordx4 v[148:149], off
	s_add_i32 m0, s58, 0x2000
	s_add_u32 s58, s8, 0x40000
	v_lshl_add_u64 v[154:155], s[8:9], 0, v[142:143]
	s_addc_u32 s59, s9, 0
	s_add_i32 s60, s54, s35
	global_load_lds_dwordx4 v[154:155], off
	v_lshl_add_u64 v[158:159], s[58:59], 0, v[138:139]
	s_mov_b32 m0, s60
	v_lshl_add_u64 v[162:163], s[10:11], 0, v[140:141]
	global_load_lds_dwordx4 v[158:159], off
	v_lshl_add_u64 v[158:159], s[58:59], 0, v[142:143]
	s_add_i32 m0, s60, 0x2000
	s_nop 0
	global_load_lds_dwordx4 v[158:159], off
	v_lshl_add_u64 v[158:159], s[10:11], 0, v[136:137]
	s_mov_b32 m0, s36
	s_nop 0
	global_load_lds_dwordx4 v[158:159], off
	s_mov_b32 m0, s37
	s_nop 0
	global_load_lds_dwordx4 v[162:163], off
	s_waitcnt vmcnt(24)
	s_waitcnt lgkmcnt(0)
	s_barrier
	s_setprio 1
	s_waitcnt lgkmcnt(0)
	v_mfma_f32_16x16x32_bf16 v[60:63], v[144:147], v[216:219], v[60:63]
	v_mfma_f32_16x16x32_bf16 v[56:59], v[176:179], v[216:219], v[56:59]
	v_mfma_f32_16x16x32_bf16 v[44:47], v[144:147], v[224:227], v[44:47]
	v_mfma_f32_16x16x32_bf16 v[40:43], v[176:179], v[224:227], v[40:43]
	v_mfma_f32_16x16x32_bf16 v[28:31], v[144:147], v[232:235], v[28:31]
	v_mfma_f32_16x16x32_bf16 v[24:27], v[176:179], v[232:235], v[24:27]
	v_mfma_f32_16x16x32_bf16 v[12:15], v[144:147], v[240:243], v[12:15]
	v_mfma_f32_16x16x32_bf16 v[8:11], v[176:179], v[240:243], v[8:11]
	v_mfma_f32_16x16x32_bf16 v[60:63], v[172:175], v[220:223], v[60:63]
	v_mfma_f32_16x16x32_bf16 v[56:59], v[196:199], v[220:223], v[56:59]
	v_mfma_f32_16x16x32_bf16 v[44:47], v[172:175], v[228:231], v[44:47]
	v_mfma_f32_16x16x32_bf16 v[40:43], v[196:199], v[228:231], v[40:43]
	v_mfma_f32_16x16x32_bf16 v[28:31], v[172:175], v[236:239], v[28:31]
	v_mfma_f32_16x16x32_bf16 v[24:27], v[196:199], v[236:239], v[24:27]
	v_mfma_f32_16x16x32_bf16 v[12:15], v[172:175], v[244:247], v[12:15]
	v_mfma_f32_16x16x32_bf16 v[8:11], v[196:199], v[244:247], v[8:11]
	s_setprio 0
	s_setprio 1
	v_mfma_f32_16x16x32_bf16 v[52:55], v[200:203], v[216:219], v[52:55]
	v_mfma_f32_16x16x32_bf16 v[48:51], v[208:211], v[216:219], v[48:51]
	v_mfma_f32_16x16x32_bf16 v[36:39], v[200:203], v[224:227], v[36:39]
	v_mfma_f32_16x16x32_bf16 v[32:35], v[208:211], v[224:227], v[32:35]
	v_mfma_f32_16x16x32_bf16 v[20:23], v[200:203], v[232:235], v[20:23]
	v_mfma_f32_16x16x32_bf16 v[16:19], v[208:211], v[232:235], v[16:19]
	v_mfma_f32_16x16x32_bf16 v[4:7], v[200:203], v[240:243], v[4:7]
	v_mfma_f32_16x16x32_bf16 v[0:3], v[208:211], v[240:243], v[0:3]
	v_mfma_f32_16x16x32_bf16 v[52:55], v[204:207], v[220:223], v[52:55]
	v_mfma_f32_16x16x32_bf16 v[48:51], v[212:215], v[220:223], v[48:51]
	v_mfma_f32_16x16x32_bf16 v[36:39], v[204:207], v[228:231], v[36:39]
	v_mfma_f32_16x16x32_bf16 v[32:35], v[212:215], v[228:231], v[32:35]
	v_mfma_f32_16x16x32_bf16 v[20:23], v[204:207], v[236:239], v[20:23]
	v_mfma_f32_16x16x32_bf16 v[16:19], v[212:215], v[236:239], v[16:19]
	v_mfma_f32_16x16x32_bf16 v[4:7], v[204:207], v[244:247], v[4:7]
	v_mfma_f32_16x16x32_bf16 v[0:3], v[212:215], v[244:247], v[0:3]
	s_setprio 0
	s_barrier
; #define PG8_STAGE(bufoff, gbase, voff) do { _Pragma("unroll") for (int _i = 0; _i < 2; ++_i) \
;         __builtin_amdgcn_global_load_lds((const unsigned*)((const char*)(gbase) + (voff)[_i]), (PG8_LAS unsigned*)(lds + (bufoff) + ldsw + _i * 8192), 16, 0, 0); } while (0)
; #define PG8_LDA(dst, b, h) do { _Pragma("unroll") for (int m = 0; m < 4; ++m) _Pragma("unroll") for (int k = 0; k < 2; ++k) dst[m][k] = *(const PG8_LAS bf16x8*)(lds + PG8_SA(b, h) + aoff + m * 2048 + k * 1024); } while (0)
; #define PG8_LDB(dst, b, h) do { _Pragma("unroll") for (int n = 0; n < 2; ++n) _Pragma("unroll") for (int k = 0; k < 2; ++k) dst[n][k] = *(const PG8_LAS bf16x8*)(lds + PG8_SB(b, h) + boff + n * 2048 + k * 1024); } while (0)
; #define PG8_MMA(ai, bj, At, Bt) do { __builtin_amdgcn_s_setprio(1); _Pragma("unroll") for (int m = 0; m < 4; ++m) _Pragma("unroll") for (int n = 0; n < 2; ++n) _Pragma("unroll") for (int k = 0; k < 2; ++k) \
;         acc[ai][bj][m][n] = __builtin_amdgcn_mfma_f32_16x16x32_bf16(Bt[n][k], At[m][k], acc[ai][bj][m][n], 0, 0, 0); __builtin_amdgcn_s_setprio(0); } while (0)
; #define PG8_WAIT_V(n) asm volatile("s_waitcnt vmcnt(" #n ")" ::: "memory")
; #define PG8_WAIT_L(n) asm volatile("s_waitcnt lgkmcnt(" #n ")" ::: "memory")
; #define PG8_BAR __builtin_amdgcn_s_barrier()
; #define PG8_SCHED __builtin_amdgcn_sched_barrier(0)
; template <class Epi, class Sched, bool ALIGN_EPI = false, bool SP2 = false>
; __device__ __forceinline__ void gemm_phase(PG8_LAS unsigned char* lds, const Gemm g, const Sched& S, const Epi& E) {
;     ...
;             PG8_LDB(B0, 1, 0); PG8_LDB(B1, 1, 1); PG8_SCHED; PG8_LDA(At, 1, 0); PG8_STAGE(PG8_SA(0, 1), a2 + hstep, voffA);
;             PG8_WAIT_V(8); PG8_WAIT_L(0); PG8_BAR; PG8_MMA(0, 0, At, B0); PG8_MMA(0, 1, At, B1); PG8_BAR; PG8_SCHED;
	s_add_i32 s58, 0, 0x18000
	v_add_u32_e32 v150, s58, v153
	s_add_i32 s59, 0, 0x1c000
	ds_read_b128 v[144:147], v150
	ds_read_b128 v[172:175], v150 offset:1024
	ds_read_b128 v[176:179], v150 offset:2048
	ds_read_b128 v[196:199], v150 offset:3072
	v_add_u32_e32 v150, s59, v153
	ds_read_b128 v[200:203], v150
	ds_read_b128 v[204:207], v150 offset:1024
	ds_read_b128 v[208:211], v150 offset:2048
	ds_read_b128 v[212:215], v150 offset:3072
	s_add_u32 s10, s10, 0x40000
	s_addc_u32 s11, s11, 0
	s_mov_b32 m0, s38
	v_lshl_add_u64 v[166:167], s[10:11], 0, v[136:137]
	ds_read_b128 v[216:219], v169 offset:32768
	ds_read_b128 v[220:223], v169 offset:33792
	ds_read_b128 v[224:227], v169 offset:34816
	ds_read_b128 v[228:231], v169 offset:35840
	ds_read_b128 v[232:235], v169 offset:36864
	ds_read_b128 v[236:239], v169 offset:37888
	ds_read_b128 v[240:243], v169 offset:38912
	ds_read_b128 v[244:247], v169 offset:39936
	global_load_lds_dwordx4 v[166:167], off
	v_lshl_add_u64 v[166:167], s[10:11], 0, v[140:141]
	s_mov_b32 m0, s39
	s_nop 0
	global_load_lds_dwordx4 v[166:167], off
	s_waitcnt vmcnt(8)
	s_waitcnt lgkmcnt(0)
	s_barrier
	s_setprio 1
	s_waitcnt lgkmcnt(0)
	v_mfma_f32_16x16x32_bf16 v[124:127], v[144:147], v[216:219], v[124:127]
	v_mfma_f32_16x16x32_bf16 v[120:123], v[176:179], v[216:219], v[120:123]
	v_mfma_f32_16x16x32_bf16 v[108:111], v[144:147], v[224:227], v[108:111]
	v_mfma_f32_16x16x32_bf16 v[104:107], v[176:179], v[224:227], v[104:107]
	v_mfma_f32_16x16x32_bf16 v[92:95], v[144:147], v[232:235], v[92:95]
	v_mfma_f32_16x16x32_bf16 v[88:91], v[176:179], v[232:235], v[88:91]
	v_mfma_f32_16x16x32_bf16 v[76:79], v[144:147], v[240:243], v[76:79]
	v_mfma_f32_16x16x32_bf16 v[72:75], v[176:179], v[240:243], v[72:75]
	v_mfma_f32_16x16x32_bf16 v[124:127], v[172:175], v[220:223], v[124:127]
	v_mfma_f32_16x16x32_bf16 v[120:123], v[196:199], v[220:223], v[120:123]
	v_mfma_f32_16x16x32_bf16 v[108:111], v[172:175], v[228:231], v[108:111]
	v_mfma_f32_16x16x32_bf16 v[104:107], v[196:199], v[228:231], v[104:107]
	v_mfma_f32_16x16x32_bf16 v[92:95], v[172:175], v[236:239], v[92:95]
	v_mfma_f32_16x16x32_bf16 v[88:91], v[196:199], v[236:239], v[88:91]
	v_mfma_f32_16x16x32_bf16 v[76:79], v[172:175], v[244:247], v[76:79]
	v_mfma_f32_16x16x32_bf16 v[72:75], v[196:199], v[244:247], v[72:75]
	s_setprio 0
	s_setprio 1
	v_mfma_f32_16x16x32_bf16 v[116:119], v[200:203], v[216:219], v[116:119]
	v_mfma_f32_16x16x32_bf16 v[112:115], v[208:211], v[216:219], v[112:115]
	v_mfma_f32_16x16x32_bf16 v[100:103], v[200:203], v[224:227], v[100:103]
	v_mfma_f32_16x16x32_bf16 v[96:99], v[208:211], v[224:227], v[96:99]
	v_mfma_f32_16x16x32_bf16 v[84:87], v[200:203], v[232:235], v[84:87]
	v_mfma_f32_16x16x32_bf16 v[80:83], v[208:211], v[232:235], v[80:83]
	v_mfma_f32_16x16x32_bf16 v[68:71], v[200:203], v[240:243], v[68:71]
	v_mfma_f32_16x16x32_bf16 v[64:67], v[208:211], v[240:243], v[64:67]
	v_mfma_f32_16x16x32_bf16 v[116:119], v[204:207], v[220:223], v[116:119]
	v_mfma_f32_16x16x32_bf16 v[112:115], v[212:215], v[220:223], v[112:115]
	v_mfma_f32_16x16x32_bf16 v[100:103], v[204:207], v[228:231], v[100:103]
	v_mfma_f32_16x16x32_bf16 v[96:99], v[212:215], v[228:231], v[96:99]
	v_mfma_f32_16x16x32_bf16 v[84:87], v[204:207], v[236:239], v[84:87]
	v_mfma_f32_16x16x32_bf16 v[80:83], v[212:215], v[236:239], v[80:83]
	v_mfma_f32_16x16x32_bf16 v[68:71], v[204:207], v[244:247], v[68:71]
	v_mfma_f32_16x16x32_bf16 v[64:67], v[212:215], v[244:247], v[64:67]
	s_setprio 0
	s_barrier
; #define PG8_STAGE(bufoff, gbase, voff) do { _Pragma("unroll") for (int _i = 0; _i < 2; ++_i) \
;         __builtin_amdgcn_global_load_lds((const unsigned*)((const char*)(gbase) + (voff)[_i]), (PG8_LAS unsigned*)(lds + (bufoff) + ldsw + _i * 8192), 16, 0, 0); } while (0)
; #define PG8_LDA(dst, b, h) do { _Pragma("unroll") for (int m = 0; m < 4; ++m) _Pragma("unroll") for (int k = 0; k < 2; ++k) dst[m][k] = *(const PG8_LAS bf16x8*)(lds + PG8_SA(b, h) + aoff + m * 2048 + k * 1024); } while (0)
; #define PG8_MMA(ai, bj, At, Bt) do { __builtin_amdgcn_s_setprio(1); _Pragma("unroll") for (int m = 0; m < 4; ++m) _Pragma("unroll") for (int n = 0; n < 2; ++n) _Pragma("unroll") for (int k = 0; k < 2; ++k) \
;         acc[ai][bj][m][n] = __builtin_amdgcn_mfma_f32_16x16x32_bf16(Bt[n][k], At[m][k], acc[ai][bj][m][n], 0, 0, 0); __builtin_amdgcn_s_setprio(0); } while (0)
; #define PG8_WAIT_V(n) asm volatile("s_waitcnt vmcnt(" #n ")" ::: "memory")
; #define PG8_WAIT_L(n) asm volatile("s_waitcnt lgkmcnt(" #n ")" ::: "memory")
; #define PG8_BAR __builtin_amdgcn_s_barrier()
; #define PG8_SCHED __builtin_amdgcn_sched_barrier(0)
; template <class Epi, class Sched, bool ALIGN_EPI = false, bool SP2 = false>
; __device__ __forceinline__ void gemm_phase(PG8_LAS unsigned char* lds, const Gemm g, const Sched& S, const Epi& E) {
;     ...
;         for (int t = 0; t < nt; t += 2) {
;     ...
;             PG8_LDA(At, 1, 1); PG8_STAGE(PG8_SB(1, 0), b3, voffB); PG8_STAGE(PG8_SB(1, 1), b3 + hstep, voffB); PG8_STAGE(PG8_SA(1, 0), a3, voffA);
;             PG8_WAIT_V(8); PG8_WAIT_L(0); PG8_BAR; PG8_MMA(1, 0, At, B0); PG8_MMA(1, 1, At, B1); PG8_BAR; PG8_SCHED;
	s_add_i32 s10, s58, s35
	v_lshl_add_u64 v[148:149], v[148:149], 0, s[16:17]
	s_mov_b32 m0, s10
	ds_read_b128 v[216:219], v169 offset:49152
	ds_read_b128 v[220:223], v169 offset:50176
	ds_read_b128 v[224:227], v169 offset:51200
	ds_read_b128 v[228:231], v169 offset:52224
	ds_read_b128 v[232:235], v169 offset:53248
	ds_read_b128 v[236:239], v169 offset:54272
	ds_read_b128 v[240:243], v169 offset:55296
	ds_read_b128 v[244:247], v169 offset:56320
	global_load_lds_dwordx4 v[148:149], off
	s_add_i32 m0, s10, 0x2000
	s_add_u32 s8, s8, 0x40080
	v_lshl_add_u64 v[148:149], v[154:155], 0, s[16:17]
	s_addc_u32 s9, s9, 0
	s_add_i32 s10, s59, s35
	global_load_lds_dwordx4 v[148:149], off
	v_lshl_add_u64 v[148:149], s[8:9], 0, v[138:139]
	s_mov_b32 m0, s10
	s_nop 0
	global_load_lds_dwordx4 v[148:149], off
	v_lshl_add_u64 v[148:149], s[8:9], 0, v[142:143]
	s_add_i32 m0, s10, 0x2000
	s_nop 0
	global_load_lds_dwordx4 v[148:149], off
	v_lshl_add_u64 v[148:149], v[158:159], 0, s[16:17]
	s_mov_b32 m0, s49
	s_nop 0
	global_load_lds_dwordx4 v[148:149], off
	v_lshl_add_u64 v[148:149], v[162:163], 0, s[16:17]
	s_mov_b32 m0, s50
	s_nop 0
	global_load_lds_dwordx4 v[148:149], off
	s_waitcnt vmcnt(8)
	s_waitcnt lgkmcnt(0)
	s_barrier
	s_setprio 1
	s_waitcnt lgkmcnt(0)
	v_mfma_f32_16x16x32_bf16 v[60:63], v[144:147], v[216:219], v[60:63]
	v_mfma_f32_16x16x32_bf16 v[56:59], v[176:179], v[216:219], v[56:59]
	v_mfma_f32_16x16x32_bf16 v[44:47], v[144:147], v[224:227], v[44:47]
	v_mfma_f32_16x16x32_bf16 v[40:43], v[176:179], v[224:227], v[40:43]
	v_mfma_f32_16x16x32_bf16 v[28:31], v[144:147], v[232:235], v[28:31]
	v_mfma_f32_16x16x32_bf16 v[24:27], v[176:179], v[232:235], v[24:27]
	v_mfma_f32_16x16x32_bf16 v[12:15], v[144:147], v[240:243], v[12:15]
	v_mfma_f32_16x16x32_bf16 v[8:11], v[176:179], v[240:243], v[8:11]
	v_mfma_f32_16x16x32_bf16 v[60:63], v[172:175], v[220:223], v[60:63]
	v_mfma_f32_16x16x32_bf16 v[56:59], v[196:199], v[220:223], v[56:59]
	v_mfma_f32_16x16x32_bf16 v[44:47], v[172:175], v[228:231], v[44:47]
	v_mfma_f32_16x16x32_bf16 v[40:43], v[196:199], v[228:231], v[40:43]
	v_mfma_f32_16x16x32_bf16 v[28:31], v[172:175], v[236:239], v[28:31]
	v_mfma_f32_16x16x32_bf16 v[24:27], v[196:199], v[236:239], v[24:27]
	v_mfma_f32_16x16x32_bf16 v[12:15], v[172:175], v[244:247], v[12:15]
	v_mfma_f32_16x16x32_bf16 v[8:11], v[196:199], v[244:247], v[8:11]
	s_setprio 0
	s_setprio 1
	v_mfma_f32_16x16x32_bf16 v[52:55], v[200:203], v[216:219], v[52:55]
	v_mfma_f32_16x16x32_bf16 v[48:51], v[208:211], v[216:219], v[48:51]
	v_mfma_f32_16x16x32_bf16 v[36:39], v[200:203], v[224:227], v[36:39]
	v_mfma_f32_16x16x32_bf16 v[32:35], v[208:211], v[224:227], v[32:35]
	v_mfma_f32_16x16x32_bf16 v[20:23], v[200:203], v[232:235], v[20:23]
	v_mfma_f32_16x16x32_bf16 v[16:19], v[208:211], v[232:235], v[16:19]
	v_mfma_f32_16x16x32_bf16 v[4:7], v[200:203], v[240:243], v[4:7]
	v_mfma_f32_16x16x32_bf16 v[0:3], v[208:211], v[240:243], v[0:3]
	v_mfma_f32_16x16x32_bf16 v[52:55], v[204:207], v[220:223], v[52:55]
	v_mfma_f32_16x16x32_bf16 v[48:51], v[212:215], v[220:223], v[48:51]
	v_mfma_f32_16x16x32_bf16 v[36:39], v[204:207], v[228:231], v[36:39]
	v_mfma_f32_16x16x32_bf16 v[32:35], v[212:215], v[228:231], v[32:35]
	v_mfma_f32_16x16x32_bf16 v[20:23], v[204:207], v[236:239], v[20:23]
	v_mfma_f32_16x16x32_bf16 v[16:19], v[212:215], v[236:239], v[16:19]
	v_mfma_f32_16x16x32_bf16 v[4:7], v[204:207], v[244:247], v[4:7]
	v_mfma_f32_16x16x32_bf16 v[0:3], v[212:215], v[244:247], v[0:3]
	s_setprio 0
	s_barrier
	s_add_i32 s57, s57, 2
	s_add_u32 s6, s6, 0x100
	s_addc_u32 s7, s7, 0
	s_add_u32 s23, s23, 0x100
	s_addc_u32 s25, s25, 0
	s_cmp_gt_u32 s57, 13
	s_cbranch_scc0 .LBB0_967
